# adds: GLA staging loads use four per-lane offset sets, one base advance per four tokens
# baseline (speedup 1.0000x reference)
.LBB0_1315:
	s_lshl_b32 s10, s53, 2
	s_ashr_i32 s11, s53, 6
	s_and_b32 s10, s10, 28
	s_and_b32 s62, s11, 3
	s_add_i32 s31, s10, s11
	s_and_b32 s10, s53, 32
	s_bfe_i32 s63, s53, 0x10005
	s_lshl_b32 s84, s62, 8
	s_cmp_eq_u32 s10, 0
	s_cselect_b64 s[70:71], -1, 0
	s_and_b64 s[10:11], s[70:71], exec
	s_movk_i32 s11, 0xc00
	s_cselect_b32 s56, s11, 0x1000
	v_readlane_b32 s11, v253, 40
	v_readlane_b32 s57, v252, 53
	s_cselect_b32 s11, s57, s11
	v_readlane_b32 s57, v253, 39
	s_cselect_b32 s10, 1, -1
	s_cselect_b32 s74, s96, s57
	s_add_u32 s56, s34, s56
	s_addc_u32 s57, s35, 0
	s_add_u32 s56, s56, s84
	s_addc_u32 s57, s57, 0
	s_lshl_b32 s75, s62, 9
	v_readlane_b32 s62, v253, 49
	s_add_u32 s62, s62, s75
	v_readlane_b32 s64, v253, 50
	s_addc_u32 s65, s64, 0
	s_lshl_b32 s72, s53, 4
	s_and_b32 s77, s72, 0x180
	s_add_u32 s72, s62, s77
	s_addc_u32 s73, s65, 0
	s_ashr_i32 s65, s31, 2
	v_lshl_add_u64 v[46:47], v[30:31], 1, s[56:57]
	s_lshl_b32 s56, s65, 8
	s_add_i32 s56, s56, 0x10000
	s_and_b32 s31, s63, 0xff
	s_or_b32 s76, s56, s31
	s_waitcnt vmcnt(0)
	v_mov_b32_e32 v20, s76
	v_mad_i32_i24 v110, s10, v52, s10
	v_mad_i32_i24 v2, s10, v52, v20
	v_add_u32_e32 v111, s10, v110
	v_ashrrev_i32_e32 v3, 31, v2
	v_add_u32_e32 v8, s76, v110
	v_add_u32_e32 v14, s76, v111
	v_lshlrev_b64 v[2:3], 13, v[2:3]
	v_ashrrev_i32_e32 v9, 31, v8
	v_ashrrev_i32_e32 v15, 31, v14
	v_add_u32_e32 v112, s10, v111
	v_lshl_add_u64 v[42:43], v[34:35], 0, s[84:85]
	v_lshl_add_u64 v[44:45], v[36:37], 0, s[84:85]
	v_lshl_add_u64 v[4:5], v[46:47], 0, v[2:3]
	v_lshlrev_b64 v[8:9], 13, v[8:9]
	v_lshlrev_b64 v[14:15], 13, v[14:15]
	v_add_u32_e32 v113, s10, v112
	v_lshl_add_u64 v[6:7], v[44:45], 0, v[2:3]
	v_lshl_add_u64 v[2:3], v[42:43], 0, v[2:3]
	v_lshl_add_u64 v[10:11], v[46:47], 0, v[8:9]
	v_lshl_add_u64 v[12:13], v[44:45], 0, v[8:9]
	v_lshl_add_u64 v[8:9], v[42:43], 0, v[8:9]
	v_lshl_add_u64 v[16:17], v[46:47], 0, v[14:15]
	v_lshl_add_u64 v[18:19], v[44:45], 0, v[14:15]
	global_load_dword v115, v[4:5], off
	global_load_dword v116, v[6:7], off
	global_load_dword v118, v[2:3], off
	global_load_dword v119, v[10:11], off
	global_load_dword v121, v[12:13], off
	global_load_dword v122, v[8:9], off
	global_load_dword v124, v[16:17], off
	global_load_dword v127, v[18:19], off
	v_add_u32_e32 v4, s76, v112
	v_add_u32_e32 v114, s10, v113
	v_ashrrev_i32_e32 v5, 31, v4
	v_add_u32_e32 v10, s76, v113
	v_add_u32_e32 v16, s76, v114
	v_lshlrev_b64 v[4:5], 13, v[4:5]
	v_ashrrev_i32_e32 v11, 31, v10
	v_ashrrev_i32_e32 v17, 31, v16
	v_lshl_add_u64 v[2:3], v[42:43], 0, v[14:15]
	v_lshl_add_u64 v[6:7], v[46:47], 0, v[4:5]
	v_lshlrev_b64 v[10:11], 13, v[10:11]
	v_lshlrev_b64 v[16:17], 13, v[16:17]
	v_add_u32_e32 v117, s10, v114
	v_lshl_add_u64 v[8:9], v[44:45], 0, v[4:5]
	v_lshl_add_u64 v[4:5], v[42:43], 0, v[4:5]
	v_lshl_add_u64 v[12:13], v[46:47], 0, v[10:11]
	v_lshl_add_u64 v[14:15], v[44:45], 0, v[10:11]
	v_lshl_add_u64 v[10:11], v[42:43], 0, v[10:11]
	v_lshl_add_u64 v[18:19], v[46:47], 0, v[16:17]
	global_load_dword v130, v[2:3], off
	global_load_dword v132, v[6:7], off
	global_load_dword v133, v[8:9], off
	global_load_dword v135, v[4:5], off
	global_load_dword v136, v[12:13], off
	global_load_dword v137, v[14:15], off
	global_load_dword v138, v[10:11], off
	global_load_dword v143, v[18:19], off
	v_add_u32_e32 v6, s76, v117
	v_add_u32_e32 v120, s10, v117
	v_ashrrev_i32_e32 v7, 31, v6
	v_add_u32_e32 v12, s76, v120
	v_lshlrev_b64 v[6:7], 13, v[6:7]
	v_ashrrev_i32_e32 v13, 31, v12
	v_add_u32_e32 v123, s10, v120
	v_lshl_add_u64 v[2:3], v[44:45], 0, v[16:17]
	v_lshl_add_u64 v[8:9], v[46:47], 0, v[6:7]
	v_lshlrev_b64 v[12:13], 13, v[12:13]
	v_add_u32_e32 v125, s10, v123
	v_lshl_add_u64 v[4:5], v[42:43], 0, v[16:17]
	v_lshl_add_u64 v[10:11], v[44:45], 0, v[6:7]
	v_lshl_add_u64 v[6:7], v[42:43], 0, v[6:7]
	v_lshl_add_u64 v[14:15], v[46:47], 0, v[12:13]
	v_lshl_add_u64 v[16:17], v[44:45], 0, v[12:13]
	v_lshl_add_u64 v[12:13], v[42:43], 0, v[12:13]
	global_load_dword v144, v[2:3], off
	global_load_dword v145, v[4:5], off
	global_load_dword v146, v[8:9], off
	global_load_dword v147, v[10:11], off
	global_load_dword v148, v[6:7], off
	global_load_dword v149, v[14:15], off
	global_load_dword v150, v[16:17], off
	global_load_dword v151, v[12:13], off
	v_add_u32_e32 v2, s76, v123
	v_add_u32_e32 v8, s76, v125
	v_add_u32_e32 v126, s10, v125
	v_ashrrev_i32_e32 v3, 31, v2
	v_ashrrev_i32_e32 v9, 31, v8
	v_add_u32_e32 v14, s76, v126
	v_lshlrev_b64 v[2:3], 13, v[2:3]
	v_lshlrev_b64 v[8:9], 13, v[8:9]
	v_ashrrev_i32_e32 v15, 31, v14
	v_add_u32_e32 v128, s10, v126
	v_lshl_add_u64 v[4:5], v[46:47], 0, v[2:3]
	v_lshl_add_u64 v[10:11], v[46:47], 0, v[8:9]
	v_lshlrev_b64 v[14:15], 13, v[14:15]
	v_add_u32_e32 v129, s10, v128
	v_lshl_add_u64 v[6:7], v[44:45], 0, v[2:3]
	v_lshl_add_u64 v[2:3], v[42:43], 0, v[2:3]
	v_lshl_add_u64 v[12:13], v[44:45], 0, v[8:9]
	v_lshl_add_u64 v[8:9], v[42:43], 0, v[8:9]
	v_lshl_add_u64 v[16:17], v[46:47], 0, v[14:15]
	v_lshl_add_u64 v[18:19], v[44:45], 0, v[14:15]
	global_load_dword v152, v[4:5], off
	global_load_dword v153, v[6:7], off
	global_load_dword v154, v[2:3], off
	global_load_dword v155, v[10:11], off
	global_load_dword v156, v[12:13], off
	global_load_dword v157, v[8:9], off
	global_load_dword v158, v[16:17], off
	global_load_dword v159, v[18:19], off
	v_add_u32_e32 v4, s76, v128
	v_add_u32_e32 v10, s76, v129
	v_add_u32_e32 v131, s10, v129
	v_ashrrev_i32_e32 v5, 31, v4
	v_ashrrev_i32_e32 v11, 31, v10
	v_add_u32_e32 v16, s76, v131
	v_lshlrev_b64 v[4:5], 13, v[4:5]
	v_lshlrev_b64 v[10:11], 13, v[10:11]
	v_ashrrev_i32_e32 v17, 31, v16
	v_lshl_add_u64 v[2:3], v[42:43], 0, v[14:15]
	v_lshl_add_u64 v[6:7], v[46:47], 0, v[4:5]
	v_lshl_add_u64 v[12:13], v[46:47], 0, v[10:11]
	v_lshlrev_b64 v[16:17], 13, v[16:17]
	v_add_u32_e32 v134, s10, v131
	v_lshl_add_u64 v[8:9], v[44:45], 0, v[4:5]
	v_lshl_add_u64 v[4:5], v[42:43], 0, v[4:5]
	v_lshl_add_u64 v[14:15], v[44:45], 0, v[10:11]
	v_lshl_add_u64 v[10:11], v[42:43], 0, v[10:11]
	v_lshl_add_u64 v[18:19], v[46:47], 0, v[16:17]
	global_load_dword v160, v[2:3], off
	global_load_dword v161, v[6:7], off
	global_load_dword v162, v[8:9], off
	global_load_dword v163, v[4:5], off
	global_load_dword v164, v[12:13], off
	global_load_dword v165, v[14:15], off
	global_load_dword v166, v[10:11], off
	global_load_dword v167, v[18:19], off
	v_add_u32_e32 v6, s76, v134
	v_mad_i32_i24 v12, s10, v63, v20
	v_ashrrev_i32_e32 v7, 31, v6
	v_ashrrev_i32_e32 v13, 31, v12
	v_lshl_add_u64 v[2:3], v[44:45], 0, v[16:17]
	v_lshlrev_b64 v[6:7], 13, v[6:7]
	v_lshlrev_b64 v[12:13], 13, v[12:13]
	v_lshl_add_u64 v[4:5], v[42:43], 0, v[16:17]
	v_lshl_add_u64 v[8:9], v[46:47], 0, v[6:7]
	v_lshl_add_u64 v[10:11], v[44:45], 0, v[6:7]
	v_lshl_add_u64 v[6:7], v[42:43], 0, v[6:7]
	v_lshl_add_u64 v[14:15], v[46:47], 0, v[12:13]
	v_lshl_add_u64 v[16:17], v[44:45], 0, v[12:13]
	v_lshl_add_u64 v[12:13], v[42:43], 0, v[12:13]
	global_load_dword v168, v[2:3], off
	global_load_dword v169, v[4:5], off
	global_load_dword v170, v[8:9], off
	global_load_dword v171, v[10:11], off
	global_load_dword v172, v[6:7], off
	global_load_dword v173, v[14:15], off
	global_load_dword v174, v[16:17], off
	global_load_dword v175, v[12:13], off
	v_mad_i32_i24 v2, s10, v33, v20
	v_ashrrev_i32_e32 v3, 31, v2
	v_lshl_add_u64 v[48:49], v[38:39], 1, s[72:73]
	v_lshlrev_b64 v[2:3], 13, v[2:3]
	v_lshl_add_u64 v[2:3], v[48:49], 0, v[2:3]
	global_load_dwordx4 v[18:21], v[2:3], off
	s_lshl_b32 s65, s65, 13
	s_add_u32 s31, s74, s75
	s_addc_u32 s11, s11, 0
	s_add_u32 s31, s31, s77
	s_addc_u32 s11, s11, 0
	s_add_u32 s62, s31, s52
	s_addc_u32 s63, s11, 0
	v_mov_b32_e32 v41, v0
	v_mov_b32_e32 v2, 0
	s_mov_b32 s57, 0
	v_mul_i32_i24_e32 v139, s10, v52
	v_mul_i32_i24_e32 v140, s10, v63
	v_mul_i32_i24_e32 v141, s10, v33
	v_lshl_add_u64 v[50:51], s[62:63], 0, v[40:41]
	v_mul_lo_u32 v41, s10, v91
	v_mul_lo_u32 v142, s10, v96
	s_movk_i32 s74, 0xff40
	s_movk_i32 s75, 0x20bf
	v_mov_b32_e32 v3, v2
	v_mov_b32_e32 v4, v2
	v_mov_b32_e32 v5, v2
	v_mov_b32_e32 v14, v2
	v_mov_b32_e32 v15, v2
	v_mov_b32_e32 v16, v2
	v_mov_b32_e32 v17, v2
	v_mov_b32_e32 v6, v2
	v_mov_b32_e32 v7, v2
	v_mov_b32_e32 v8, v2
	v_mov_b32_e32 v9, v2
	v_mov_b32_e32 v10, v2
	v_mov_b32_e32 v11, v2
	v_mov_b32_e32 v12, v2
	v_mov_b32_e32 v13, v2
	v_readfirstlane_b32 s82, v42
	v_readfirstlane_b32 s83, v43
	s_cmp_lg_u32 s70, 0
	s_cselect_b32 s91, 0, 0xffffffcd
	s_cselect_b32 s32, 0, 0xffffffc1
	s_cselect_b32 s78, 0, 0xffffffd0
	s_cselect_b32 s99, 0, -1
	s_mov_b32 s98, 0x8000
	s_cselect_b32 s98, s98, 0xffff8000
	v_subrev_u32_e32 v134, s78, v139
	v_subrev_u32_e32 v113, s32, v141
	v_lshlrev_b32_e32 v134, 13, v134
	v_lshlrev_b32_e32 v113, 13, v113
	v_subrev_u32_e32 v110, s82, v46
	v_subrev_u32_e32 v111, s82, v44
	v_subrev_u32_e32 v112, s82, v42
	v_add_u32_e32 v113, v113, v48
	v_add_u32_e32 v110, v110, v134
	v_add_u32_e32 v111, v111, v134
	v_add_u32_e32 v112, v112, v134
	v_subrev_u32_e32 v113, s82, v113
	s_movk_i32 s32, 0x2000
	s_cselect_b32 s32, s32, 0x4000
	s_movk_i32 s78, 0x4000
	s_cselect_b32 s78, s78, 0x2000
	v_add_u32_e32 v114, s32, v110
	v_add_u32_e32 v117, s32, v111
	v_add_u32_e32 v120, s32, v112
	v_add_u32_e32 v123, s78, v110
	v_add_u32_e32 v125, s78, v111
	v_add_u32_e32 v126, s78, v112
	s_cselect_b32 s32, 0x6000, 0
	s_cselect_b32 s78, 0, 0x6000
	v_add_u32_e32 v128, s32, v110
	v_add_u32_e32 v129, s32, v111
	v_add_u32_e32 v131, s32, v112
	v_add_u32_e32 v110, s78, v110
	v_add_u32_e32 v111, s78, v111
	v_add_u32_e32 v112, s78, v112
	s_branch .LBB0_1317

.LBB0_1317:
	s_waitcnt vmcnt(45)
	v_perm_b32 v26, v115, v115, v32
	v_add_f32_e32 v176, 0, v26
	v_perm_b32 v26, v119, v119, v32
	v_add_f32_e32 v177, v176, v26
	s_waitcnt vmcnt(39)
	v_perm_b32 v26, v124, v124, v32
	v_add_f32_e32 v178, v177, v26
	v_perm_b32 v26, v132, v132, v32
	v_add_f32_e32 v179, v178, v26
	s_waitcnt vmcnt(33)
	v_perm_b32 v26, v136, v136, v32
	v_add_f32_e32 v180, v179, v26
	v_perm_b32 v26, v143, v143, v32
	v_add_f32_e32 v181, v180, v26
	s_waitcnt vmcnt(27)
	v_perm_b32 v26, v146, v146, v32
	v_add_f32_e32 v182, v181, v26
	v_perm_b32 v26, v149, v149, v32
	v_add_f32_e32 v183, v182, v26
	s_waitcnt vmcnt(21)
	v_perm_b32 v26, v152, v152, v32
	v_add_f32_e32 v184, v183, v26
	v_perm_b32 v26, v155, v155, v32
	v_add_f32_e32 v185, v184, v26
	s_waitcnt vmcnt(15)
	v_perm_b32 v26, v158, v158, v32
	v_add_f32_e32 v186, v185, v26
	v_perm_b32 v26, v161, v161, v32
	v_add_f32_e32 v187, v186, v26
	s_waitcnt vmcnt(9)
	v_perm_b32 v26, v164, v164, v32
	v_add_f32_e32 v188, v187, v26
	v_perm_b32 v26, v167, v167, v32
	v_add_f32_e32 v189, v188, v26
	s_waitcnt vmcnt(3)
	v_perm_b32 v26, v170, v170, v32
	v_add_f32_e32 v190, v189, v26
	v_perm_b32 v26, v173, v173, v32
	v_add_f32_e32 v191, v190, v26
	ds_bpermute_b32 v26, v53, v191
	ds_bpermute_b32 v28, v54, v191
	ds_bpermute_b32 v27, v55, v191
	ds_bpermute_b32 v29, v56, v191
	v_cvt_pk_bf16_f32 v22, v2, v3
	v_cvt_pk_bf16_f32 v23, v4, v5
	v_cvt_pk_bf16_f32 v24, v14, v15
	v_cvt_pk_bf16_f32 v25, v16, v17
	s_add_i32 s78, s74, 0x100
	s_add_i32 s32, s75, 0xffffe000
	s_cmp_lg_u32 s70, 0
	s_cselect_b32 s78, s78, s32
	s_cselect_b32 s32, s74, s75
	s_add_i32 s32, s32, s65
	s_add_i32 s78, s78, s56
	s_cmp_gt_u32 s57, 2
	s_cselect_b32 s32, s32, s78
	s_cmp_eq_u32 s75, -1
	s_cselect_b32 s32, s76, s32
	s_add_i32 s32, s32, s91
	s_lshl_b32 s32, s32, 13
	s_add_u32 s80, s82, s32
	s_addc_u32 s81, s83, 0
	s_waitcnt lgkmcnt(0)
	s_barrier
	ds_write2_b64 v103, v[22:23], v[24:25] offset1:4
	v_cvt_pk_bf16_f32 v22, v6, v7
	v_cvt_pk_bf16_f32 v23, v8, v9
	v_cvt_pk_bf16_f32 v24, v10, v11
	v_cvt_pk_bf16_f32 v25, v12, v13
	ds_write2_b64 v103, v[22:23], v[24:25] offset0:8 offset1:12
	v_cndmask_b32_e64 v22, v26, 0, s[0:1]
	v_cndmask_b32_e64 v23, 0, v28, s[2:3]
	v_add_f32_e32 v22, v22, v23
	v_cndmask_b32_e64 v23, 0, v27, s[4:5]
	v_add_f32_e32 v192, v22, v23
	v_pk_add_f32 v[22:23], v[26:27], v[28:29]
	v_add_f32_e32 v22, v22, v23
	v_add_f32_e32 v23, v176, v192
	v_exp_f32_e32 v25, v23
	v_perm_b32 v24, v116, v116, v32
	v_exp_f32_e64 v26, -v23
	v_exp_f32_e32 v22, v22
	v_mul_f32_e32 v23, v25, v24
	v_cvt_pk_bf16_f32 v23, v23, s0
	ds_write_b16 v64, v23
	v_add_f32_e32 v23, v177, v192
	v_exp_f32_e32 v24, v23
	v_exp_f32_e64 v27, -v23
	v_perm_b32 v25, v121, v121, v32
	v_perm_b32 v29, v122, v122, v1
	v_perm_b32 v28, v118, v118, v32
	global_load_dword v115, v110, s[80:81]
	global_load_dword v116, v111, s[80:81]
	global_load_dword v118, v112, s[80:81]
	global_load_dword v119, v114, s[80:81]
	global_load_dword v121, v117, s[80:81]
	global_load_dword v122, v120, s[80:81]
	v_mul_f32_e32 v23, v24, v25
	v_mul_f32_e32 v24, v26, v28
	v_cvt_pk_bf16_f32 v23, v23, s0
	v_cvt_pk_bf16_f32 v24, v24, s0
	ds_write_b16 v64, v24 offset:17408
	v_pk_mul_f32 v[24:25], v[22:23], v[26:27] op_sel_hi:[0,1]
	ds_write_b16 v65, v23
	v_mul_f32_e32 v23, v27, v29
	v_cvt_pk_bf16_f32 v23, v23, s0
	ds_write_b16 v65, v23 offset:17408
	v_add_f32_e32 v23, v178, v192
	v_pk_mul_f32 v[24:25], v[24:25], v[28:29]
	v_exp_f32_e32 v28, v23
	v_perm_b32 v27, v127, v127, v32
	v_exp_f32_e64 v26, -v23
	v_mul_f32_e32 v23, v28, v27
	v_cvt_pk_bf16_f32 v23, v23, s0
	ds_write_b16 v66, v23
	v_add_f32_e32 v23, v179, v192
	v_exp_f32_e32 v28, v23
	v_perm_b32 v177, v133, v133, v32
	v_exp_f32_e64 v27, -v23
	v_mul_f32_e32 v23, v28, v177
	v_perm_b32 v28, v130, v130, v32
	global_load_dword v124, v123, s[80:81]
	global_load_dword v127, v125, s[80:81]
	global_load_dword v130, v126, s[80:81]
	v_mul_f32_e32 v176, v26, v28
	v_cvt_pk_bf16_f32 v23, v23, s0
	v_perm_b32 v29, v135, v135, v1
	global_load_dword v132, v128, s[80:81]
	global_load_dword v133, v129, s[80:81]
	global_load_dword v135, v131, s[80:81]
	s_add_u32 s80, s80, s98
	s_addc_u32 s81, s81, s99
	v_cvt_pk_bf16_f32 v176, v176, s0
	ds_write_b16 v66, v176 offset:17408
	v_pk_mul_f32 v[176:177], v[22:23], v[26:27] op_sel_hi:[0,1]
	ds_write_b16 v67, v23
	v_mul_f32_e32 v23, v27, v29
	v_cvt_pk_bf16_f32 v23, v23, s0
	ds_write_b16 v67, v23 offset:17408
	v_add_f32_e32 v23, v180, v192
	v_pk_mul_f32 v[176:177], v[176:177], v[28:29]
	v_exp_f32_e32 v28, v23
	v_perm_b32 v27, v137, v137, v32
	v_exp_f32_e64 v26, -v23
	v_mul_f32_e32 v23, v28, v27
	v_cvt_pk_bf16_f32 v23, v23, s0
	ds_write_b16 v68, v23
	v_add_f32_e32 v23, v181, v192
	v_exp_f32_e32 v28, v23
	v_perm_b32 v179, v144, v144, v32
	v_exp_f32_e64 v27, -v23
	v_mul_f32_e32 v23, v28, v179
	v_perm_b32 v28, v138, v138, v32
	global_load_dword v136, v110, s[80:81]
	global_load_dword v137, v111, s[80:81]
	global_load_dword v138, v112, s[80:81]
	v_mul_f32_e32 v178, v26, v28
	v_cvt_pk_bf16_f32 v23, v23, s0
	v_perm_b32 v29, v145, v145, v1
	global_load_dword v143, v114, s[80:81]
	global_load_dword v144, v117, s[80:81]
	global_load_dword v145, v120, s[80:81]
	v_cvt_pk_bf16_f32 v178, v178, s0
	ds_write_b16 v68, v178 offset:17408
	v_pk_mul_f32 v[178:179], v[22:23], v[26:27] op_sel_hi:[0,1]
	ds_write_b16 v69, v23
	v_mul_f32_e32 v23, v27, v29
	v_cvt_pk_bf16_f32 v23, v23, s0
	ds_write_b16 v69, v23 offset:17408
	v_add_f32_e32 v23, v182, v192
	v_pk_mul_f32 v[178:179], v[178:179], v[28:29]
	v_exp_f32_e32 v28, v23
	v_perm_b32 v27, v147, v147, v32
	v_exp_f32_e64 v26, -v23
	v_mul_f32_e32 v23, v28, v27
	v_cvt_pk_bf16_f32 v23, v23, s0
	ds_write_b16 v70, v23
	v_add_f32_e32 v23, v183, v192
	v_exp_f32_e32 v28, v23
	v_perm_b32 v181, v150, v150, v32
	v_exp_f32_e64 v27, -v23
	v_mul_f32_e32 v23, v28, v181
	v_perm_b32 v28, v148, v148, v32
	global_load_dword v146, v123, s[80:81]
	global_load_dword v147, v125, s[80:81]
	global_load_dword v148, v126, s[80:81]
	v_mul_f32_e32 v180, v26, v28
	v_cvt_pk_bf16_f32 v23, v23, s0
	v_perm_b32 v29, v151, v151, v1
	global_load_dword v149, v128, s[80:81]
	global_load_dword v150, v129, s[80:81]
	global_load_dword v151, v131, s[80:81]
	s_add_u32 s80, s80, s98
	s_addc_u32 s81, s81, s99
	v_cvt_pk_bf16_f32 v180, v180, s0
	ds_write_b16 v70, v180 offset:17408
	v_pk_mul_f32 v[180:181], v[22:23], v[26:27] op_sel_hi:[0,1]
	ds_write_b16 v71, v23
	v_mul_f32_e32 v23, v27, v29
	v_cvt_pk_bf16_f32 v23, v23, s0
	ds_write_b16 v71, v23 offset:17408
	v_add_f32_e32 v23, v184, v192
	v_pk_mul_f32 v[180:181], v[180:181], v[28:29]
	v_exp_f32_e32 v28, v23
	v_perm_b32 v27, v153, v153, v32
	v_exp_f32_e64 v26, -v23
	v_mul_f32_e32 v23, v28, v27
	v_cvt_pk_bf16_f32 v23, v23, s0
	ds_write_b16 v72, v23
	v_add_f32_e32 v23, v185, v192
	v_exp_f32_e32 v28, v23
	v_perm_b32 v183, v156, v156, v32
	v_exp_f32_e64 v27, -v23
	v_mul_f32_e32 v23, v28, v183
	v_perm_b32 v28, v154, v154, v32
	global_load_dword v152, v110, s[80:81]
	global_load_dword v153, v111, s[80:81]
	global_load_dword v154, v112, s[80:81]
	v_mul_f32_e32 v182, v26, v28
	v_cvt_pk_bf16_f32 v23, v23, s0
	v_perm_b32 v29, v157, v157, v1
	global_load_dword v155, v114, s[80:81]
	global_load_dword v156, v117, s[80:81]
	global_load_dword v157, v120, s[80:81]
	v_cvt_pk_bf16_f32 v182, v182, s0
	ds_write_b16 v72, v182 offset:17408
	v_pk_mul_f32 v[182:183], v[22:23], v[26:27] op_sel_hi:[0,1]
	ds_write_b16 v73, v23
	v_mul_f32_e32 v23, v27, v29
	v_cvt_pk_bf16_f32 v23, v23, s0
	ds_write_b16 v73, v23 offset:17408
	v_add_f32_e32 v23, v186, v192
	v_pk_mul_f32 v[182:183], v[182:183], v[28:29]
	v_exp_f32_e32 v28, v23
	v_perm_b32 v27, v159, v159, v32
	v_exp_f32_e64 v26, -v23
	v_mul_f32_e32 v23, v28, v27
	v_cvt_pk_bf16_f32 v23, v23, s0
	ds_write_b16 v74, v23
	v_add_f32_e32 v23, v187, v192
	v_exp_f32_e32 v28, v23
	v_perm_b32 v185, v162, v162, v32
	v_exp_f32_e64 v27, -v23
	v_mul_f32_e32 v23, v28, v185
	v_perm_b32 v28, v160, v160, v32
	global_load_dword v158, v123, s[80:81]
	global_load_dword v159, v125, s[80:81]
	global_load_dword v160, v126, s[80:81]
	v_mul_f32_e32 v184, v26, v28
	v_cvt_pk_bf16_f32 v23, v23, s0
	v_perm_b32 v29, v163, v163, v1
	global_load_dword v161, v128, s[80:81]
	global_load_dword v162, v129, s[80:81]
	global_load_dword v163, v131, s[80:81]
	s_add_u32 s80, s80, s98
	s_addc_u32 s81, s81, s99
	v_cvt_pk_bf16_f32 v184, v184, s0
	ds_write_b16 v74, v184 offset:17408
	v_pk_mul_f32 v[184:185], v[22:23], v[26:27] op_sel_hi:[0,1]
	ds_write_b16 v75, v23
	v_mul_f32_e32 v23, v27, v29
	v_cvt_pk_bf16_f32 v23, v23, s0
	ds_write_b16 v75, v23 offset:17408
	v_add_f32_e32 v23, v188, v192
	v_pk_mul_f32 v[184:185], v[184:185], v[28:29]
	v_exp_f32_e32 v28, v23
	v_perm_b32 v27, v165, v165, v32
	v_exp_f32_e64 v26, -v23
	v_mul_f32_e32 v23, v28, v27
	v_cvt_pk_bf16_f32 v23, v23, s0
	ds_write_b16 v76, v23
	v_add_f32_e32 v23, v189, v192
	v_exp_f32_e32 v28, v23
	v_perm_b32 v187, v168, v168, v32
	v_exp_f32_e64 v27, -v23
	v_mul_f32_e32 v23, v28, v187
	v_perm_b32 v28, v166, v166, v32
	global_load_dword v164, v110, s[80:81]
	global_load_dword v165, v111, s[80:81]
	global_load_dword v166, v112, s[80:81]
	v_mul_f32_e32 v186, v26, v28
	v_cvt_pk_bf16_f32 v23, v23, s0
	v_perm_b32 v29, v169, v169, v1
	global_load_dword v167, v114, s[80:81]
	global_load_dword v168, v117, s[80:81]
	global_load_dword v169, v120, s[80:81]
	v_cvt_pk_bf16_f32 v186, v186, s0
	ds_write_b16 v76, v186 offset:17408
	v_pk_mul_f32 v[186:187], v[22:23], v[26:27] op_sel_hi:[0,1]
	ds_write_b16 v77, v23
	v_mul_f32_e32 v23, v27, v29
	v_cvt_pk_bf16_f32 v23, v23, s0
	ds_write_b16 v77, v23 offset:17408
	v_add_f32_e32 v23, v190, v192
	v_exp_f32_e32 v27, v23
	v_perm_b32 v26, v171, v171, v32
	v_pk_mul_f32 v[186:187], v[186:187], v[28:29]
	v_exp_f32_e64 v28, -v23
	v_mul_f32_e32 v23, v27, v26
	v_cvt_pk_bf16_f32 v23, v23, s0
	ds_write_b16 v78, v23
	v_add_f32_e32 v23, v191, v192
	v_exp_f32_e32 v26, v23
	s_waitcnt vmcnt(43)
	v_exp_f32_e64 v29, -v23
	v_perm_b32 v27, v174, v174, v32
	v_perm_b32 v189, v175, v175, v1
	v_perm_b32 v188, v172, v172, v32
	global_load_dword v170, v123, s[80:81]
	global_load_dword v171, v125, s[80:81]
	global_load_dword v172, v126, s[80:81]
	global_load_dword v173, v128, s[80:81]
	global_load_dword v174, v129, s[80:81]
	global_load_dword v175, v131, s[80:81]
	v_mul_f32_e32 v23, v26, v27
	v_mul_f32_e32 v26, v28, v188
	v_cvt_pk_bf16_f32 v23, v23, s0
	v_cvt_pk_bf16_f32 v26, v26, s0
	ds_write_b16 v78, v26 offset:17408
	ds_write_b16 v79, v23
	v_mul_f32_e32 v23, v29, v189
	v_cvt_pk_bf16_f32 v23, v23, s0
	v_pk_mul_f32 v[28:29], v[22:23], v[28:29] op_sel_hi:[0,1]
	v_cvt_pk_bf16_f32 v24, v24, v25
	v_cvt_pk_bf16_f32 v25, v176, v177
	v_cvt_pk_bf16_f32 v26, v178, v179
	v_cvt_pk_bf16_f32 v27, v180, v181
	v_pk_mul_f32 v[28:29], v[28:29], v[188:189]
	ds_write_b16 v79, v23 offset:17408
	v_cvt_pk_bf16_f32 v176, v182, v183
	v_cvt_pk_bf16_f32 v177, v184, v185
	v_cvt_pk_bf16_f32 v178, v186, v187
	v_cvt_pk_bf16_f32 v179, v28, v29
	ds_write_b128 v57, v[24:27] offset:34816
	ds_write_b128 v57, v[176:179] offset:34832
	s_and_saveexec_b64 s[72:73], s[0:1]
	ds_write_b32 v61, v22
	s_or_b64 exec, exec, s[72:73]
	s_cmp_eq_u32 s75, -1
	s_mov_b32 s10, s76
	s_waitcnt vmcnt(48)
	ds_write_b16 v58, v18 offset:53248
	ds_write_b16_d16_hi v58, v18 offset:53392
	ds_write_b16 v58, v19 offset:53536
	ds_write_b16_d16_hi v58, v19 offset:53680
	ds_write_b16 v58, v20 offset:53824
	ds_write_b16_d16_hi v58, v20 offset:53968
	ds_write_b16 v58, v21 offset:54112
	ds_write_b16_d16_hi v59, v21 offset:53248
	s_cbranch_scc1 .LBB0_1325
	s_cmp_gt_u32 s57, 2
	s_mov_b64 s[72:73], -1
	s_cbranch_scc0 .LBB0_1322
	s_and_b64 s[10:11], s[70:71], exec
	s_cselect_b32 s10, s74, s75
	s_add_i32 s10, s10, s65
	s_mov_b64 s[72:73], 0

.LBB0_1324:
	s_and_b64 s[72:73], s[70:71], exec
	s_cselect_b32 s72, 0xfffe8000, 0
	s_cselect_b32 s73, -1, 0
	s_add_u32 s80, s80, s72
	s_addc_u32 s81, s81, s73
	global_load_dwordx4 v[18:21], v113, s[80:81]
